# hand-written software-pipelined weight transposer (phase 0 part c), two items in flight per wave
# speedup vs baseline: 1.0136x; 1.0084x over previous
.LBB0_130:
	s_or_b64 exec, exec, s[0:1]
	s_load_dwordx2 s[0:1], s[92:93], 0x58
	s_load_dwordx2 s[2:3], s[92:93], 0xb8
	s_load_dwordx2 s[4:5], s[92:93], 0xc0
	s_load_dwordx2 s[6:7], s[92:93], 0xc8
	s_load_dwordx2 s[8:9], s[92:93], 0xd0
	s_load_dwordx2 s[10:11], s[92:93], 0xe8
	v_and_b32_e32 v74, 63, v154
	v_lshrrev_b32_e32 v75, 6, v154
	v_mul_u32_u24_e32 v75, 0x2100, v75
	v_lshrrev_b32_e32 v3, 5, v74
	v_and_b32_e32 v4, 31, v74
	v_lshlrev_b32_e32 v4, 2, v4
	v_lshrrev_b32_e32 v5, 3, v74
	v_and_b32_e32 v6, 7, v74
	v_mul_u32_u24_e32 v2, 264, v6
	v_add_u32_e32 v2, v2, v5
	v_lshl_add_u32 v2, v2, 2, v75
	v_lshlrev_b32_e32 v6, 4, v6
	v_mul_u32_u24_e32 v1, 132, v3
	v_add3_u32 v1, v1, v4, v75
	v_readfirstlane_b32 s13, v154
	s_lshr_b32 s13, s13, 6
	s_lshl_b32 s26, s96, 3
	s_add_u32 s13, s13, s26
	s_mov_b32 s12, s13
	s_waitcnt lgkmcnt(0)
	s_cmp_ge_u32 s12, 33280
	s_cselect_b32 s41, 1, 0
	s_cselect_b32 s26, 33280, 0
	s_sub_u32 s42, s12, s26
	s_cmp_ge_u32 s42, 12288
	s_cbranch_scc1 .Ltr_m2
	s_mul_i32 s43, s42, 43691
	s_lshr_b32 s43, s43, 24
	s_mul_i32 s26, s43, 384
	s_sub_u32 s44, s42, s26
	s_mov_b32 s14, s0
	s_mov_b32 s15, s1
	s_mov_b32 s36, 0xc000
	s_mov_b32 s37, 0x6000000
	s_mov_b32 s38, 0x0
	s_mov_b32 s39, 0x3000000
	s_mov_b32 s40, 0x1000
	s_branch .Ltr_dec_done1
.Ltr_m2:
	s_cmp_ge_u32 s42, 13312
	s_cbranch_scc1 .Ltr_m3
	s_sub_u32 s42, s42, 12288
	s_lshr_b32 s43, s42, 6
	s_and_b32 s44, s42, 63
	s_mov_b32 s14, s2
	s_mov_b32 s15, s3
	s_mov_b32 s36, 0x2000
	s_mov_b32 s37, 0x800000
	s_mov_b32 s38, 0x6000000
	s_mov_b32 s39, 0x400000
	s_mov_b32 s40, 0x800
	s_branch .Ltr_dec_done1
.Ltr_m3:
	s_cmp_ge_u32 s42, 14336
	s_cbranch_scc1 .Ltr_m4
	s_sub_u32 s42, s42, 13312
	s_lshr_b32 s43, s42, 6
	s_and_b32 s44, s42, 63
	s_mov_b32 s14, s4
	s_mov_b32 s15, s5
	s_mov_b32 s36, 0x2000
	s_mov_b32 s37, 0x800000
	s_mov_b32 s38, 0x6800000
	s_mov_b32 s39, 0x400000
	s_mov_b32 s40, 0x800
	s_branch .Ltr_dec_done1
.Ltr_m4:
	s_cmp_ge_u32 s42, 16384
	s_cbranch_scc1 .Ltr_m5
	s_sub_u32 s42, s42, 14336
	s_lshr_b32 s43, s42, 6
	s_and_b32 s44, s42, 63
	s_mov_b32 s14, s6
	s_mov_b32 s15, s7
	s_mov_b32 s36, 0x2000
	s_mov_b32 s37, 0x1000000
	s_mov_b32 s38, 0x7000000
	s_mov_b32 s39, 0x800000
	s_mov_b32 s40, 0x1000
	s_branch .Ltr_dec_done1
.Ltr_m5:
	s_cmp_ge_u32 s42, 27648
	s_cbranch_scc1 .Ltr_m6
	s_sub_u32 s42, s42, 16384
	s_mul_i32 s43, s42, 47663
	s_lshr_b32 s43, s43, 24
	s_mul_i32 s26, s43, 352
	s_sub_u32 s44, s42, s26
	s_mov_b32 s14, s8
	s_mov_b32 s15, s9
	s_mov_b32 s36, 0xb000
	s_mov_b32 s37, 0x5800000
	s_mov_b32 s38, 0x8000000
	s_mov_b32 s39, 0x2c00000
	s_mov_b32 s40, 0x1000
	s_branch .Ltr_dec_done1
.Ltr_m6:
	s_sub_u32 s42, s42, 27648
	s_lshr_b32 s43, s42, 6
	s_and_b32 s44, s42, 63
	s_mov_b32 s14, s10
	s_mov_b32 s15, s11
	s_mov_b32 s36, 0x2000
	s_mov_b32 s37, 0x2c00000
	s_mov_b32 s38, 0xd800000
	s_mov_b32 s39, 0x1600000
	s_mov_b32 s40, 0x2c00
.Ltr_dec_done1:
	s_mul_i32 s26, s41, s37
	s_lshl_b32 s27, s43, 6
	s_mul_i32 s27, s27, s36
	s_add_u32 s26, s26, s27
	s_lshl_b32 s27, s44, 7
	s_add_u32 s26, s26, s27
	s_add_u32 s14, s14, s26
	s_addc_u32 s15, s15, 0
	s_mul_i32 s26, s41, s39
	s_add_u32 s26, s26, s38
	s_lshl_b32 s27, s44, 5
	s_mul_i32 s27, s27, s40
	s_add_u32 s26, s26, s27
	s_lshl_b32 s27, s43, 7
	s_add_u32 s26, s26, s27
	s_add_u32 s18, s90, s26
	s_addc_u32 s19, s91, 0
	s_mov_b32 s22, s40
	v_mad_u32_u24 v7, v3, s36, v4
	s_lshl_b32 s45, s36, 1
	global_load_dword v10, v7, s[14:15]
	s_add_u32 s14, s14, s45
	s_addc_u32 s15, s15, 0
	global_load_dword v11, v7, s[14:15]
	s_add_u32 s14, s14, s45
	s_addc_u32 s15, s15, 0
	global_load_dword v12, v7, s[14:15]
	s_add_u32 s14, s14, s45
	s_addc_u32 s15, s15, 0
	global_load_dword v13, v7, s[14:15]
	s_add_u32 s14, s14, s45
	s_addc_u32 s15, s15, 0
	global_load_dword v14, v7, s[14:15]
	s_add_u32 s14, s14, s45
	s_addc_u32 s15, s15, 0
	global_load_dword v15, v7, s[14:15]
	s_add_u32 s14, s14, s45
	s_addc_u32 s15, s15, 0
	global_load_dword v16, v7, s[14:15]
	s_add_u32 s14, s14, s45
	s_addc_u32 s15, s15, 0
	global_load_dword v17, v7, s[14:15]
	s_add_u32 s14, s14, s45
	s_addc_u32 s15, s15, 0
	global_load_dword v18, v7, s[14:15]
	s_add_u32 s14, s14, s45
	s_addc_u32 s15, s15, 0
	global_load_dword v19, v7, s[14:15]
	s_add_u32 s14, s14, s45
	s_addc_u32 s15, s15, 0
	global_load_dword v20, v7, s[14:15]
	s_add_u32 s14, s14, s45
	s_addc_u32 s15, s15, 0
	global_load_dword v21, v7, s[14:15]
	s_add_u32 s14, s14, s45
	s_addc_u32 s15, s15, 0
	global_load_dword v22, v7, s[14:15]
	s_add_u32 s14, s14, s45
	s_addc_u32 s15, s15, 0
	global_load_dword v23, v7, s[14:15]
	s_add_u32 s14, s14, s45
	s_addc_u32 s15, s15, 0
	global_load_dword v24, v7, s[14:15]
	s_add_u32 s14, s14, s45
	s_addc_u32 s15, s15, 0
	global_load_dword v25, v7, s[14:15]
	s_add_u32 s14, s14, s45
	s_addc_u32 s15, s15, 0
	global_load_dword v26, v7, s[14:15]
	s_add_u32 s14, s14, s45
	s_addc_u32 s15, s15, 0
	global_load_dword v27, v7, s[14:15]
	s_add_u32 s14, s14, s45
	s_addc_u32 s15, s15, 0
	global_load_dword v28, v7, s[14:15]
	s_add_u32 s14, s14, s45
	s_addc_u32 s15, s15, 0
	global_load_dword v29, v7, s[14:15]
	s_add_u32 s14, s14, s45
	s_addc_u32 s15, s15, 0
	global_load_dword v30, v7, s[14:15]
	s_add_u32 s14, s14, s45
	s_addc_u32 s15, s15, 0
	global_load_dword v31, v7, s[14:15]
	s_add_u32 s14, s14, s45
	s_addc_u32 s15, s15, 0
	global_load_dword v32, v7, s[14:15]
	s_add_u32 s14, s14, s45
	s_addc_u32 s15, s15, 0
	global_load_dword v33, v7, s[14:15]
	s_add_u32 s14, s14, s45
	s_addc_u32 s15, s15, 0
	global_load_dword v34, v7, s[14:15]
	s_add_u32 s14, s14, s45
	s_addc_u32 s15, s15, 0
	global_load_dword v35, v7, s[14:15]
	s_add_u32 s14, s14, s45
	s_addc_u32 s15, s15, 0
	global_load_dword v36, v7, s[14:15]
	s_add_u32 s14, s14, s45
	s_addc_u32 s15, s15, 0
	global_load_dword v37, v7, s[14:15]
	s_add_u32 s14, s14, s45
	s_addc_u32 s15, s15, 0
	global_load_dword v38, v7, s[14:15]
	s_add_u32 s14, s14, s45
	s_addc_u32 s15, s15, 0
	global_load_dword v39, v7, s[14:15]
	s_add_u32 s14, s14, s45
	s_addc_u32 s15, s15, 0
	global_load_dword v40, v7, s[14:15]
	s_add_u32 s14, s14, s45
	s_addc_u32 s15, s15, 0
	global_load_dword v41, v7, s[14:15]
.Ltr_loop:
	s_add_u32 s12, s12, 2048
	s_cmp_lt_u32 s12, 66560
	s_cselect_b32 s24, 1, 0
	s_cbranch_scc0 .Ltr_nonext8
	s_cmp_ge_u32 s12, 33280
	s_cselect_b32 s41, 1, 0
	s_cselect_b32 s26, 33280, 0
	s_sub_u32 s42, s12, s26
	s_cmp_ge_u32 s42, 12288
	s_cbranch_scc1 .Ltr_m11
	s_mul_i32 s43, s42, 43691
	s_lshr_b32 s43, s43, 24
	s_mul_i32 s26, s43, 384
	s_sub_u32 s44, s42, s26
	s_mov_b32 s16, s0
	s_mov_b32 s17, s1
	s_mov_b32 s36, 0xc000
	s_mov_b32 s37, 0x6000000
	s_mov_b32 s38, 0x0
	s_mov_b32 s39, 0x3000000
	s_mov_b32 s40, 0x1000
	s_branch .Ltr_dec_done10
.Ltr_m11:
	s_cmp_ge_u32 s42, 13312
	s_cbranch_scc1 .Ltr_m12
	s_sub_u32 s42, s42, 12288
	s_lshr_b32 s43, s42, 6
	s_and_b32 s44, s42, 63
	s_mov_b32 s16, s2
	s_mov_b32 s17, s3
	s_mov_b32 s36, 0x2000
	s_mov_b32 s37, 0x800000
	s_mov_b32 s38, 0x6000000
	s_mov_b32 s39, 0x400000
	s_mov_b32 s40, 0x800
	s_branch .Ltr_dec_done10
.Ltr_m12:
	s_cmp_ge_u32 s42, 14336
	s_cbranch_scc1 .Ltr_m13
	s_sub_u32 s42, s42, 13312
	s_lshr_b32 s43, s42, 6
	s_and_b32 s44, s42, 63
	s_mov_b32 s16, s4
	s_mov_b32 s17, s5
	s_mov_b32 s36, 0x2000
	s_mov_b32 s37, 0x800000
	s_mov_b32 s38, 0x6800000
	s_mov_b32 s39, 0x400000
	s_mov_b32 s40, 0x800
	s_branch .Ltr_dec_done10
.Ltr_m13:
	s_cmp_ge_u32 s42, 16384
	s_cbranch_scc1 .Ltr_m14
	s_sub_u32 s42, s42, 14336
	s_lshr_b32 s43, s42, 6
	s_and_b32 s44, s42, 63
	s_mov_b32 s16, s6
	s_mov_b32 s17, s7
	s_mov_b32 s36, 0x2000
	s_mov_b32 s37, 0x1000000
	s_mov_b32 s38, 0x7000000
	s_mov_b32 s39, 0x800000
	s_mov_b32 s40, 0x1000
	s_branch .Ltr_dec_done10
.Ltr_m14:
	s_cmp_ge_u32 s42, 27648
	s_cbranch_scc1 .Ltr_m15
	s_sub_u32 s42, s42, 16384
	s_mul_i32 s43, s42, 47663
	s_lshr_b32 s43, s43, 24
	s_mul_i32 s26, s43, 352
	s_sub_u32 s44, s42, s26
	s_mov_b32 s16, s8
	s_mov_b32 s17, s9
	s_mov_b32 s36, 0xb000
	s_mov_b32 s37, 0x5800000
	s_mov_b32 s38, 0x8000000
	s_mov_b32 s39, 0x2c00000
	s_mov_b32 s40, 0x1000
	s_branch .Ltr_dec_done10
.Ltr_m15:
	s_sub_u32 s42, s42, 27648
	s_lshr_b32 s43, s42, 6
	s_and_b32 s44, s42, 63
	s_mov_b32 s16, s10
	s_mov_b32 s17, s11
	s_mov_b32 s36, 0x2000
	s_mov_b32 s37, 0x2c00000
	s_mov_b32 s38, 0xd800000
	s_mov_b32 s39, 0x1600000
	s_mov_b32 s40, 0x2c00
.Ltr_dec_done10:
	s_mul_i32 s26, s41, s37
	s_lshl_b32 s27, s43, 6
	s_mul_i32 s27, s27, s36
	s_add_u32 s26, s26, s27
	s_lshl_b32 s27, s44, 7
	s_add_u32 s26, s26, s27
	s_add_u32 s16, s16, s26
	s_addc_u32 s17, s17, 0
	s_mul_i32 s26, s41, s39
	s_add_u32 s26, s26, s38
	s_lshl_b32 s27, s44, 5
	s_mul_i32 s27, s27, s40
	s_add_u32 s26, s26, s27
	s_lshl_b32 s27, s43, 7
	s_add_u32 s26, s26, s27
	s_add_u32 s20, s90, s26
	s_addc_u32 s21, s91, 0
	s_mov_b32 s23, s40
	v_mad_u32_u24 v8, v3, s36, v4
	s_lshl_b32 s45, s36, 1
	global_load_dword v42, v8, s[16:17]
	s_add_u32 s16, s16, s45
	s_addc_u32 s17, s17, 0
	global_load_dword v43, v8, s[16:17]
	s_add_u32 s16, s16, s45
	s_addc_u32 s17, s17, 0
	global_load_dword v44, v8, s[16:17]
	s_add_u32 s16, s16, s45
	s_addc_u32 s17, s17, 0
	global_load_dword v45, v8, s[16:17]
	s_add_u32 s16, s16, s45
	s_addc_u32 s17, s17, 0
	global_load_dword v46, v8, s[16:17]
	s_add_u32 s16, s16, s45
	s_addc_u32 s17, s17, 0
	global_load_dword v47, v8, s[16:17]
	s_add_u32 s16, s16, s45
	s_addc_u32 s17, s17, 0
	global_load_dword v48, v8, s[16:17]
	s_add_u32 s16, s16, s45
	s_addc_u32 s17, s17, 0
	global_load_dword v49, v8, s[16:17]
	s_add_u32 s16, s16, s45
	s_addc_u32 s17, s17, 0
	global_load_dword v50, v8, s[16:17]
	s_add_u32 s16, s16, s45
	s_addc_u32 s17, s17, 0
	global_load_dword v51, v8, s[16:17]
	s_add_u32 s16, s16, s45
	s_addc_u32 s17, s17, 0
	global_load_dword v52, v8, s[16:17]
	s_add_u32 s16, s16, s45
	s_addc_u32 s17, s17, 0
	global_load_dword v53, v8, s[16:17]
	s_add_u32 s16, s16, s45
	s_addc_u32 s17, s17, 0
	global_load_dword v54, v8, s[16:17]
	s_add_u32 s16, s16, s45
	s_addc_u32 s17, s17, 0
	global_load_dword v55, v8, s[16:17]
	s_add_u32 s16, s16, s45
	s_addc_u32 s17, s17, 0
	global_load_dword v56, v8, s[16:17]
	s_add_u32 s16, s16, s45
	s_addc_u32 s17, s17, 0
	global_load_dword v57, v8, s[16:17]
	s_add_u32 s16, s16, s45
	s_addc_u32 s17, s17, 0
	global_load_dword v58, v8, s[16:17]
	s_add_u32 s16, s16, s45
	s_addc_u32 s17, s17, 0
	global_load_dword v59, v8, s[16:17]
	s_add_u32 s16, s16, s45
	s_addc_u32 s17, s17, 0
	global_load_dword v60, v8, s[16:17]
	s_add_u32 s16, s16, s45
	s_addc_u32 s17, s17, 0
	global_load_dword v61, v8, s[16:17]
	s_add_u32 s16, s16, s45
	s_addc_u32 s17, s17, 0
	global_load_dword v62, v8, s[16:17]
	s_add_u32 s16, s16, s45
	s_addc_u32 s17, s17, 0
	global_load_dword v63, v8, s[16:17]
	s_add_u32 s16, s16, s45
	s_addc_u32 s17, s17, 0
	global_load_dword v64, v8, s[16:17]
	s_add_u32 s16, s16, s45
	s_addc_u32 s17, s17, 0
	global_load_dword v65, v8, s[16:17]
	s_add_u32 s16, s16, s45
	s_addc_u32 s17, s17, 0
	global_load_dword v66, v8, s[16:17]
	s_add_u32 s16, s16, s45
	s_addc_u32 s17, s17, 0
	global_load_dword v67, v8, s[16:17]
	s_add_u32 s16, s16, s45
	s_addc_u32 s17, s17, 0
	global_load_dword v68, v8, s[16:17]
	s_add_u32 s16, s16, s45
	s_addc_u32 s17, s17, 0
	global_load_dword v69, v8, s[16:17]
	s_add_u32 s16, s16, s45
	s_addc_u32 s17, s17, 0
	global_load_dword v70, v8, s[16:17]
	s_add_u32 s16, s16, s45
	s_addc_u32 s17, s17, 0
	global_load_dword v71, v8, s[16:17]
	s_add_u32 s16, s16, s45
	s_addc_u32 s17, s17, 0
	global_load_dword v72, v8, s[16:17]
	s_add_u32 s16, s16, s45
	s_addc_u32 s17, s17, 0
	global_load_dword v73, v8, s[16:17]
	s_waitcnt vmcnt(32)
	s_branch .Ltr_after9

.Ltr_after9:
	ds_write_b32 v1, v10 offset:0
	ds_write_b32 v1, v11 offset:264
	ds_write_b32 v1, v12 offset:528
	ds_write_b32 v1, v13 offset:792
	ds_write_b32 v1, v14 offset:1056
	ds_write_b32 v1, v15 offset:1320
	ds_write_b32 v1, v16 offset:1584
	ds_write_b32 v1, v17 offset:1848
	ds_write_b32 v1, v18 offset:2112
	ds_write_b32 v1, v19 offset:2376
	ds_write_b32 v1, v20 offset:2640
	ds_write_b32 v1, v21 offset:2904
	ds_write_b32 v1, v22 offset:3168
	ds_write_b32 v1, v23 offset:3432
	ds_write_b32 v1, v24 offset:3696
	ds_write_b32 v1, v25 offset:3960
	ds_write_b32 v1, v26 offset:4224
	ds_write_b32 v1, v27 offset:4488
	ds_write_b32 v1, v28 offset:4752
	ds_write_b32 v1, v29 offset:5016
	ds_write_b32 v1, v30 offset:5280
	ds_write_b32 v1, v31 offset:5544
	ds_write_b32 v1, v32 offset:5808
	ds_write_b32 v1, v33 offset:6072
	ds_write_b32 v1, v34 offset:6336
	ds_write_b32 v1, v35 offset:6600
	ds_write_b32 v1, v36 offset:6864
	ds_write_b32 v1, v37 offset:7128
	ds_write_b32 v1, v38 offset:7392
	ds_write_b32 v1, v39 offset:7656
	ds_write_b32 v1, v40 offset:7920
	ds_write_b32 v1, v41 offset:8184
	v_mad_u32_u24 v9, v5, s22, v6
	s_lshl_b32 s46, s22, 3
	s_waitcnt lgkmcnt(0)
	ds_read_b32 v74, v2 offset:0
	ds_read_b32 v75, v2 offset:132
	ds_read_b32 v76, v2 offset:264
	ds_read_b32 v77, v2 offset:396
	ds_read_b32 v78, v2 offset:528
	ds_read_b32 v79, v2 offset:660
	ds_read_b32 v80, v2 offset:792
	ds_read_b32 v81, v2 offset:924
	ds_read_b32 v82, v2 offset:32
	ds_read_b32 v83, v2 offset:164
	ds_read_b32 v84, v2 offset:296
	ds_read_b32 v85, v2 offset:428
	ds_read_b32 v86, v2 offset:560
	ds_read_b32 v87, v2 offset:692
	ds_read_b32 v88, v2 offset:824
	ds_read_b32 v89, v2 offset:956
	s_waitcnt lgkmcnt(8)
	v_cvt_pk_bf16_f32 v106, v74, v75
	v_cvt_pk_bf16_f32 v107, v76, v77
	v_cvt_pk_bf16_f32 v108, v78, v79
	v_cvt_pk_bf16_f32 v109, v80, v81
	global_store_dwordx4 v9, v[106:109], s[18:19]
	s_add_u32 s18, s18, s46
	s_addc_u32 s19, s19, 0
	ds_read_b32 v90, v2 offset:64
	ds_read_b32 v91, v2 offset:196
	ds_read_b32 v92, v2 offset:328
	ds_read_b32 v93, v2 offset:460
	ds_read_b32 v94, v2 offset:592
	ds_read_b32 v95, v2 offset:724
	ds_read_b32 v96, v2 offset:856
	ds_read_b32 v97, v2 offset:988
	s_waitcnt lgkmcnt(8)
	v_cvt_pk_bf16_f32 v110, v82, v83
	v_cvt_pk_bf16_f32 v111, v84, v85
	v_cvt_pk_bf16_f32 v112, v86, v87
	v_cvt_pk_bf16_f32 v113, v88, v89
	global_store_dwordx4 v9, v[110:113], s[18:19]
	s_add_u32 s18, s18, s46
	s_addc_u32 s19, s19, 0
	ds_read_b32 v98, v2 offset:96
	ds_read_b32 v99, v2 offset:228
	ds_read_b32 v100, v2 offset:360
	ds_read_b32 v101, v2 offset:492
	ds_read_b32 v102, v2 offset:624
	ds_read_b32 v103, v2 offset:756
	ds_read_b32 v104, v2 offset:888
	ds_read_b32 v105, v2 offset:1020
	s_waitcnt lgkmcnt(8)
	v_cvt_pk_bf16_f32 v106, v90, v91
	v_cvt_pk_bf16_f32 v107, v92, v93
	v_cvt_pk_bf16_f32 v108, v94, v95
	v_cvt_pk_bf16_f32 v109, v96, v97
	global_store_dwordx4 v9, v[106:109], s[18:19]
	s_add_u32 s18, s18, s46
	s_addc_u32 s19, s19, 0
	s_waitcnt lgkmcnt(0)
	v_cvt_pk_bf16_f32 v110, v98, v99
	v_cvt_pk_bf16_f32 v111, v100, v101
	v_cvt_pk_bf16_f32 v112, v102, v103
	v_cvt_pk_bf16_f32 v113, v104, v105
	global_store_dwordx4 v9, v[110:113], s[18:19]
	s_cmp_eq_u32 s24, 0
	s_cbranch_scc1 .Ltr_done
	s_add_u32 s12, s12, 2048
	s_cmp_lt_u32 s12, 66560
	s_cselect_b32 s24, 1, 0
	s_cbranch_scc0 .Ltr_nonext17
	s_cmp_ge_u32 s12, 33280
	s_cselect_b32 s41, 1, 0
	s_cselect_b32 s26, 33280, 0
	s_sub_u32 s42, s12, s26
	s_cmp_ge_u32 s42, 12288
	s_cbranch_scc1 .Ltr_m20
	s_mul_i32 s43, s42, 43691
	s_lshr_b32 s43, s43, 24
	s_mul_i32 s26, s43, 384
	s_sub_u32 s44, s42, s26
	s_mov_b32 s14, s0
	s_mov_b32 s15, s1
	s_mov_b32 s36, 0xc000
	s_mov_b32 s37, 0x6000000
	s_mov_b32 s38, 0x0
	s_mov_b32 s39, 0x3000000
	s_mov_b32 s40, 0x1000
	s_branch .Ltr_dec_done19

.Ltr_dec_done19:
	s_mul_i32 s26, s41, s37
	s_lshl_b32 s27, s43, 6
	s_mul_i32 s27, s27, s36
	s_add_u32 s26, s26, s27
	s_lshl_b32 s27, s44, 7
	s_add_u32 s26, s26, s27
	s_add_u32 s14, s14, s26
	s_addc_u32 s15, s15, 0
	s_mul_i32 s26, s41, s39
	s_add_u32 s26, s26, s38
	s_lshl_b32 s27, s44, 5
	s_mul_i32 s27, s27, s40
	s_add_u32 s26, s26, s27
	s_lshl_b32 s27, s43, 7
	s_add_u32 s26, s26, s27
	s_add_u32 s18, s90, s26
	s_addc_u32 s19, s91, 0
	s_mov_b32 s22, s40
	v_mad_u32_u24 v7, v3, s36, v4
	s_lshl_b32 s45, s36, 1
	global_load_dword v10, v7, s[14:15]
	s_add_u32 s14, s14, s45
	s_addc_u32 s15, s15, 0
	global_load_dword v11, v7, s[14:15]
	s_add_u32 s14, s14, s45
	s_addc_u32 s15, s15, 0
	global_load_dword v12, v7, s[14:15]
	s_add_u32 s14, s14, s45
	s_addc_u32 s15, s15, 0
	global_load_dword v13, v7, s[14:15]
	s_add_u32 s14, s14, s45
	s_addc_u32 s15, s15, 0
	global_load_dword v14, v7, s[14:15]
	s_add_u32 s14, s14, s45
	s_addc_u32 s15, s15, 0
	global_load_dword v15, v7, s[14:15]
	s_add_u32 s14, s14, s45
	s_addc_u32 s15, s15, 0
	global_load_dword v16, v7, s[14:15]
	s_add_u32 s14, s14, s45
	s_addc_u32 s15, s15, 0
	global_load_dword v17, v7, s[14:15]
	s_add_u32 s14, s14, s45
	s_addc_u32 s15, s15, 0
	global_load_dword v18, v7, s[14:15]
	s_add_u32 s14, s14, s45
	s_addc_u32 s15, s15, 0
	global_load_dword v19, v7, s[14:15]
	s_add_u32 s14, s14, s45
	s_addc_u32 s15, s15, 0
	global_load_dword v20, v7, s[14:15]
	s_add_u32 s14, s14, s45
	s_addc_u32 s15, s15, 0
	global_load_dword v21, v7, s[14:15]
	s_add_u32 s14, s14, s45
	s_addc_u32 s15, s15, 0
	global_load_dword v22, v7, s[14:15]
	s_add_u32 s14, s14, s45
	s_addc_u32 s15, s15, 0
	global_load_dword v23, v7, s[14:15]
	s_add_u32 s14, s14, s45
	s_addc_u32 s15, s15, 0
	global_load_dword v24, v7, s[14:15]
	s_add_u32 s14, s14, s45
	s_addc_u32 s15, s15, 0
	global_load_dword v25, v7, s[14:15]
	s_add_u32 s14, s14, s45
	s_addc_u32 s15, s15, 0
	global_load_dword v26, v7, s[14:15]
	s_add_u32 s14, s14, s45
	s_addc_u32 s15, s15, 0
	global_load_dword v27, v7, s[14:15]
	s_add_u32 s14, s14, s45
	s_addc_u32 s15, s15, 0
	global_load_dword v28, v7, s[14:15]
	s_add_u32 s14, s14, s45
	s_addc_u32 s15, s15, 0
	global_load_dword v29, v7, s[14:15]
	s_add_u32 s14, s14, s45
	s_addc_u32 s15, s15, 0
	global_load_dword v30, v7, s[14:15]
	s_add_u32 s14, s14, s45
	s_addc_u32 s15, s15, 0
	global_load_dword v31, v7, s[14:15]
	s_add_u32 s14, s14, s45
	s_addc_u32 s15, s15, 0
	global_load_dword v32, v7, s[14:15]
	s_add_u32 s14, s14, s45
	s_addc_u32 s15, s15, 0
	global_load_dword v33, v7, s[14:15]
	s_add_u32 s14, s14, s45
	s_addc_u32 s15, s15, 0
	global_load_dword v34, v7, s[14:15]
	s_add_u32 s14, s14, s45
	s_addc_u32 s15, s15, 0
	global_load_dword v35, v7, s[14:15]
	s_add_u32 s14, s14, s45
	s_addc_u32 s15, s15, 0
	global_load_dword v36, v7, s[14:15]
	s_add_u32 s14, s14, s45
	s_addc_u32 s15, s15, 0
	global_load_dword v37, v7, s[14:15]
	s_add_u32 s14, s14, s45
	s_addc_u32 s15, s15, 0
	global_load_dword v38, v7, s[14:15]
	s_add_u32 s14, s14, s45
	s_addc_u32 s15, s15, 0
	global_load_dword v39, v7, s[14:15]
	s_add_u32 s14, s14, s45
	s_addc_u32 s15, s15, 0
	global_load_dword v40, v7, s[14:15]
	s_add_u32 s14, s14, s45
	s_addc_u32 s15, s15, 0
	global_load_dword v41, v7, s[14:15]
	s_waitcnt vmcnt(32)
	s_branch .Ltr_after18

.Ltr_after18:
	ds_write_b32 v1, v42 offset:0
	ds_write_b32 v1, v43 offset:264
	ds_write_b32 v1, v44 offset:528
	ds_write_b32 v1, v45 offset:792
	ds_write_b32 v1, v46 offset:1056
	ds_write_b32 v1, v47 offset:1320
	ds_write_b32 v1, v48 offset:1584
	ds_write_b32 v1, v49 offset:1848
	ds_write_b32 v1, v50 offset:2112
	ds_write_b32 v1, v51 offset:2376
	ds_write_b32 v1, v52 offset:2640
	ds_write_b32 v1, v53 offset:2904
	ds_write_b32 v1, v54 offset:3168
	ds_write_b32 v1, v55 offset:3432
	ds_write_b32 v1, v56 offset:3696
	ds_write_b32 v1, v57 offset:3960
	ds_write_b32 v1, v58 offset:4224
	ds_write_b32 v1, v59 offset:4488
	ds_write_b32 v1, v60 offset:4752
	ds_write_b32 v1, v61 offset:5016
	ds_write_b32 v1, v62 offset:5280
	ds_write_b32 v1, v63 offset:5544
	ds_write_b32 v1, v64 offset:5808
	ds_write_b32 v1, v65 offset:6072
	ds_write_b32 v1, v66 offset:6336
	ds_write_b32 v1, v67 offset:6600
	ds_write_b32 v1, v68 offset:6864
	ds_write_b32 v1, v69 offset:7128
	ds_write_b32 v1, v70 offset:7392
	ds_write_b32 v1, v71 offset:7656
	ds_write_b32 v1, v72 offset:7920
	ds_write_b32 v1, v73 offset:8184
	v_mad_u32_u24 v9, v5, s23, v6
	s_lshl_b32 s46, s23, 3
	s_waitcnt lgkmcnt(0)
	ds_read_b32 v74, v2 offset:0
	ds_read_b32 v75, v2 offset:132
	ds_read_b32 v76, v2 offset:264
	ds_read_b32 v77, v2 offset:396
	ds_read_b32 v78, v2 offset:528
	ds_read_b32 v79, v2 offset:660
	ds_read_b32 v80, v2 offset:792
	ds_read_b32 v81, v2 offset:924
	ds_read_b32 v82, v2 offset:32
	ds_read_b32 v83, v2 offset:164
	ds_read_b32 v84, v2 offset:296
	ds_read_b32 v85, v2 offset:428
	ds_read_b32 v86, v2 offset:560
	ds_read_b32 v87, v2 offset:692
	ds_read_b32 v88, v2 offset:824
	ds_read_b32 v89, v2 offset:956
	s_waitcnt lgkmcnt(8)
	v_cvt_pk_bf16_f32 v106, v74, v75
	v_cvt_pk_bf16_f32 v107, v76, v77
	v_cvt_pk_bf16_f32 v108, v78, v79
	v_cvt_pk_bf16_f32 v109, v80, v81
	global_store_dwordx4 v9, v[106:109], s[20:21]
	s_add_u32 s20, s20, s46
	s_addc_u32 s21, s21, 0
	ds_read_b32 v90, v2 offset:64
	ds_read_b32 v91, v2 offset:196
	ds_read_b32 v92, v2 offset:328
	ds_read_b32 v93, v2 offset:460
	ds_read_b32 v94, v2 offset:592
	ds_read_b32 v95, v2 offset:724
	ds_read_b32 v96, v2 offset:856
	ds_read_b32 v97, v2 offset:988
	s_waitcnt lgkmcnt(8)
	v_cvt_pk_bf16_f32 v110, v82, v83
	v_cvt_pk_bf16_f32 v111, v84, v85
	v_cvt_pk_bf16_f32 v112, v86, v87
	v_cvt_pk_bf16_f32 v113, v88, v89
	global_store_dwordx4 v9, v[110:113], s[20:21]
	s_add_u32 s20, s20, s46
	s_addc_u32 s21, s21, 0
	ds_read_b32 v98, v2 offset:96
	ds_read_b32 v99, v2 offset:228
	ds_read_b32 v100, v2 offset:360
	ds_read_b32 v101, v2 offset:492
	ds_read_b32 v102, v2 offset:624
	ds_read_b32 v103, v2 offset:756
	ds_read_b32 v104, v2 offset:888
	ds_read_b32 v105, v2 offset:1020
	s_waitcnt lgkmcnt(8)
	v_cvt_pk_bf16_f32 v106, v90, v91
	v_cvt_pk_bf16_f32 v107, v92, v93
	v_cvt_pk_bf16_f32 v108, v94, v95
	v_cvt_pk_bf16_f32 v109, v96, v97
	global_store_dwordx4 v9, v[106:109], s[20:21]
	s_add_u32 s20, s20, s46
	s_addc_u32 s21, s21, 0
	s_waitcnt lgkmcnt(0)
	v_cvt_pk_bf16_f32 v110, v98, v99
	v_cvt_pk_bf16_f32 v111, v100, v101
	v_cvt_pk_bf16_f32 v112, v102, v103
	v_cvt_pk_bf16_f32 v113, v104, v105
	global_store_dwordx4 v9, v[110:113], s[20:21]
	s_cmp_eq_u32 s24, 0
	s_cbranch_scc1 .Ltr_done
	s_branch .Ltr_loop
.Ltr_done:
	s_waitcnt vmcnt(0) lgkmcnt(0)
	s_branch .LBB0_154
